# half-mode K-loops: 3 barriers per K-tile instead of 4 (vmcnt(0) at MFMA-block end), same k-inner order and rendezvous trimming
# baseline (speedup 1.0000x reference)
.LBB0_344:
	v_mfma_i32_16x16x64_i8 v[64:67], v[100:103], v[124:127], v[64:67]
	v_mfma_i32_16x16x64_i8 v[64:67], v[104:107], v[128:131], v[64:67]
	v_mfma_i32_16x16x64_i8 v[56:59], v[108:111], v[124:127], v[56:59]
	v_mfma_i32_16x16x64_i8 v[56:59], v[112:115], v[128:131], v[56:59]
	v_mfma_i32_16x16x64_i8 v[48:51], v[100:103], v[116:119], v[48:51]
	v_mfma_i32_16x16x64_i8 v[48:51], v[104:107], v[120:123], v[48:51]
	v_mfma_i32_16x16x64_i8 v[40:43], v[108:111], v[116:119], v[40:43]
	v_mfma_i32_16x16x64_i8 v[40:43], v[112:115], v[120:123], v[40:43]
	v_mfma_i32_16x16x64_i8 v[30:33], v[100:103], v[92:95], v[30:33]
	v_mfma_i32_16x16x64_i8 v[30:33], v[104:107], v[96:99], v[30:33]
	v_mfma_i32_16x16x64_i8 v[22:25], v[108:111], v[92:95], v[22:25]
	v_mfma_i32_16x16x64_i8 v[22:25], v[112:115], v[96:99], v[22:25]
	v_mfma_i32_16x16x64_i8 v[14:17], v[100:103], v[84:87], v[14:17]
	v_mfma_i32_16x16x64_i8 v[14:17], v[104:107], v[88:91], v[14:17]
	v_mfma_i32_16x16x64_i8 v[6:9], v[108:111], v[84:87], v[6:9]
	v_mfma_i32_16x16x64_i8 v[6:9], v[112:115], v[88:91], v[6:9]
	v_mfma_i32_16x16x64_i8 v[60:63], v[68:71], v[124:127], v[60:63]
	v_mfma_i32_16x16x64_i8 v[60:63], v[72:75], v[128:131], v[60:63]
	v_mfma_i32_16x16x64_i8 v[52:55], v[76:79], v[124:127], v[52:55]
	v_mfma_i32_16x16x64_i8 v[52:55], v[80:83], v[128:131], v[52:55]
	v_mfma_i32_16x16x64_i8 v[44:47], v[68:71], v[116:119], v[44:47]
	v_mfma_i32_16x16x64_i8 v[44:47], v[72:75], v[120:123], v[44:47]
	v_mfma_i32_16x16x64_i8 v[36:39], v[76:79], v[116:119], v[36:39]
	v_mfma_i32_16x16x64_i8 v[36:39], v[80:83], v[120:123], v[36:39]
	v_mfma_i32_16x16x64_i8 v[26:29], v[68:71], v[92:95], v[26:29]
	v_mfma_i32_16x16x64_i8 v[26:29], v[72:75], v[96:99], v[26:29]
	v_mfma_i32_16x16x64_i8 v[18:21], v[76:79], v[92:95], v[18:21]
	v_mfma_i32_16x16x64_i8 v[18:21], v[80:83], v[96:99], v[18:21]
	v_mfma_i32_16x16x64_i8 v[10:13], v[68:71], v[84:87], v[10:13]
	v_mfma_i32_16x16x64_i8 v[10:13], v[72:75], v[88:91], v[10:13]
	v_mfma_i32_16x16x64_i8 v[2:5], v[76:79], v[84:87], v[2:5]
	v_mfma_i32_16x16x64_i8 v[2:5], v[80:83], v[88:91], v[2:5]
	s_waitcnt vmcnt(0)
	s_barrier
	s_setprio 0
	s_mov_b32 m0, s64
	v_lshl_add_u64 v[142:143], s[34:35], 0, v[34:35]
	s_add_u32 s74, s34, 0x40000
	global_load_lds_dwordx4 v[142:143], off
	v_lshl_add_u64 v[144:145], s[34:35], 0, v[210:211]
	s_mov_b32 m0, s65
	s_addc_u32 s75, s35, 0
	global_load_lds_dwordx4 v[144:145], off
	v_lshl_add_u64 v[68:69], s[74:75], 0, v[34:35]
	s_mov_b32 m0, s66
	v_lshl_add_u64 v[146:147], s[72:73], 0, v[206:207]
	global_load_lds_dwordx4 v[68:69], off
	v_lshl_add_u64 v[68:69], s[74:75], 0, v[210:211]
	s_mov_b32 m0, s67
	v_lshl_add_u64 v[148:149], s[72:73], 0, v[208:209]
	global_load_lds_dwordx4 v[68:69], off
	s_mov_b32 m0, s63
	s_nop 0
	global_load_lds_dwordx4 v[146:147], off
	s_mov_b32 m0, s68
	s_nop 0
	global_load_lds_dwordx4 v[148:149], off
	s_barrier
	s_add_i32 s71, 0, 0x18000
	s_add_i32 s72, 0, 0x1c000
	v_add_u32_e32 v80, s71, v140
	v_add_u32_e32 v96, s72, v140
	ds_read_b128 v[68:71], v80
	ds_read_b128 v[72:75], v80 offset:1024
	ds_read_b128 v[76:79], v80 offset:2048
	ds_read_b128 v[80:83], v80 offset:3072
	ds_read_b128 v[84:87], v96
	ds_read_b128 v[88:91], v96 offset:1024
	ds_read_b128 v[92:95], v96 offset:2048
	ds_read_b128 v[96:99], v96 offset:3072
	ds_read_b128 v[100:103], v141 offset:32768
	ds_read_b128 v[104:107], v141 offset:33792
	ds_read_b128 v[108:111], v141 offset:34816
	ds_read_b128 v[112:115], v141 offset:35840
	ds_read_b128 v[116:119], v141 offset:36864
	ds_read_b128 v[120:123], v141 offset:37888
	ds_read_b128 v[124:127], v141 offset:38912
	ds_read_b128 v[128:131], v141 offset:39936
	s_waitcnt lgkmcnt(0)
	s_setprio 1
	s_barrier
	v_mfma_i32_16x16x64_i8 v[64:67], v[68:71], v[100:103], v[64:67]
	v_mfma_i32_16x16x64_i8 v[64:67], v[72:75], v[104:107], v[64:67]
	v_mfma_i32_16x16x64_i8 v[56:59], v[76:79], v[100:103], v[56:59]
	v_mfma_i32_16x16x64_i8 v[56:59], v[80:83], v[104:107], v[56:59]
	v_mfma_i32_16x16x64_i8 v[48:51], v[68:71], v[108:111], v[48:51]
	v_mfma_i32_16x16x64_i8 v[48:51], v[72:75], v[112:115], v[48:51]
	v_mfma_i32_16x16x64_i8 v[40:43], v[76:79], v[108:111], v[40:43]
	v_mfma_i32_16x16x64_i8 v[40:43], v[80:83], v[112:115], v[40:43]
	v_mfma_i32_16x16x64_i8 v[30:33], v[68:71], v[116:119], v[30:33]
	v_mfma_i32_16x16x64_i8 v[30:33], v[72:75], v[120:123], v[30:33]
	v_mfma_i32_16x16x64_i8 v[22:25], v[76:79], v[116:119], v[22:25]
	v_mfma_i32_16x16x64_i8 v[22:25], v[80:83], v[120:123], v[22:25]
	v_mfma_i32_16x16x64_i8 v[14:17], v[68:71], v[124:127], v[14:17]
	v_mfma_i32_16x16x64_i8 v[14:17], v[72:75], v[128:131], v[14:17]
	v_mfma_i32_16x16x64_i8 v[6:9], v[76:79], v[124:127], v[6:9]
	v_mfma_i32_16x16x64_i8 v[6:9], v[80:83], v[128:131], v[6:9]
	v_mfma_i32_16x16x64_i8 v[60:63], v[84:87], v[100:103], v[60:63]
	v_mfma_i32_16x16x64_i8 v[60:63], v[88:91], v[104:107], v[60:63]
	v_mfma_i32_16x16x64_i8 v[52:55], v[92:95], v[100:103], v[52:55]
	v_mfma_i32_16x16x64_i8 v[52:55], v[96:99], v[104:107], v[52:55]
	v_mfma_i32_16x16x64_i8 v[44:47], v[84:87], v[108:111], v[44:47]
	v_mfma_i32_16x16x64_i8 v[44:47], v[88:91], v[112:115], v[44:47]
	v_mfma_i32_16x16x64_i8 v[36:39], v[92:95], v[108:111], v[36:39]
	v_mfma_i32_16x16x64_i8 v[36:39], v[96:99], v[112:115], v[36:39]
	v_mfma_i32_16x16x64_i8 v[26:29], v[84:87], v[116:119], v[26:29]
	v_mfma_i32_16x16x64_i8 v[26:29], v[88:91], v[120:123], v[26:29]
	v_mfma_i32_16x16x64_i8 v[18:21], v[92:95], v[116:119], v[18:21]
	v_mfma_i32_16x16x64_i8 v[18:21], v[96:99], v[120:123], v[18:21]
	v_mfma_i32_16x16x64_i8 v[10:13], v[84:87], v[124:127], v[10:13]
	v_mfma_i32_16x16x64_i8 v[10:13], v[88:91], v[128:131], v[10:13]
	v_mfma_i32_16x16x64_i8 v[2:5], v[92:95], v[124:127], v[2:5]
	v_mfma_i32_16x16x64_i8 v[2:5], v[96:99], v[128:131], v[2:5]
	s_waitcnt vmcnt(0)
	s_barrier
	s_setprio 0
	s_add_i32 s71, s71, s62
	v_lshl_add_u64 v[68:69], v[142:143], 0, s[18:19]
	s_mov_b32 m0, s71
	s_nop 0
	global_load_lds_dwordx4 v[68:69], off
	s_add_i32 m0, s71, 0x2000
	s_add_u32 s34, s34, 0x40080
	v_lshl_add_u64 v[68:69], v[144:145], 0, s[18:19]
	s_addc_u32 s35, s35, 0
	s_add_i32 s71, s72, s62
	global_load_lds_dwordx4 v[68:69], off
	v_lshl_add_u64 v[68:69], s[34:35], 0, v[34:35]
	s_mov_b32 m0, s71
	s_nop 0
	global_load_lds_dwordx4 v[68:69], off
	v_lshl_add_u64 v[68:69], s[34:35], 0, v[210:211]
	s_add_i32 m0, s71, 0x2000
	s_nop 0
	global_load_lds_dwordx4 v[68:69], off
	v_lshl_add_u64 v[68:69], v[146:147], 0, s[18:19]
	s_mov_b32 m0, s69
	s_nop 0
	global_load_lds_dwordx4 v[68:69], off
	v_lshl_add_u64 v[68:69], v[148:149], 0, s[18:19]
	s_mov_b32 m0, s70
	s_nop 0
	global_load_lds_dwordx4 v[68:69], off
	s_barrier
	s_add_i32 s45, s45, 2
	s_add_u32 s27, s27, 0x100
	s_addc_u32 s29, s29, 0
	s_add_u32 s36, s36, 0x100
	s_addc_u32 s37, s37, 0
	s_cmp_gt_u32 s45, 13
	s_cbranch_scc1 .LBB0_347
.LBB0_345:
	v_add_u32_e32 v68, 0, v140
	v_add_u32_e32 v69, 0x10000, v68
	v_add_u32_e32 v80, 0x14000, v68
	ds_read_b128 v[100:103], v69
	ds_read_b128 v[104:107], v69 offset:1024
	ds_read_b128 v[108:111], v69 offset:2048
	ds_read_b128 v[112:115], v69 offset:3072
	ds_read_b128 v[68:71], v80
	ds_read_b128 v[72:75], v80 offset:1024
	ds_read_b128 v[76:79], v80 offset:2048
	ds_read_b128 v[80:83], v80 offset:3072
	ds_read_b128 v[124:127], v141
	ds_read_b128 v[128:131], v141 offset:1024
	ds_read_b128 v[116:119], v141 offset:2048
	ds_read_b128 v[120:123], v141 offset:3072
	ds_read_b128 v[92:95], v141 offset:4096
	ds_read_b128 v[96:99], v141 offset:5120
	ds_read_b128 v[84:87], v141 offset:6144
	ds_read_b128 v[88:91], v141 offset:7168
	s_cmp_eq_u32 s45, -2
	s_waitcnt lgkmcnt(0)
	s_cselect_b64 s[34:35], -1, 0
	s_and_b64 s[34:35], s[34:35], s[12:13]
	s_andn2_b64 vcc, exec, s[34:35]
	s_cmp_eq_u32 s45, 12
	s_cselect_b32 s73, s21, s29
	s_cselect_b32 s72, s43, s27
	s_cselect_b32 s35, s17, s37
	s_cselect_b32 s34, s44, s36
	s_setprio 1
	s_barrier
	s_cbranch_vccnz .LBB0_344
	s_add_i32 m0, s63, 0x21200
	s_nop 0
	global_load_lds_dwordx4 v[138:139], off
	s_branch .LBB0_344

.LBB0_502:
	s_add_i32 s52, 0, 0x10000
	s_cmp_eq_u32 s43, 40
	s_cselect_b32 s27, s21, s13
	s_cselect_b32 s26, s20, s11
	s_cselect_b32 s25, s23, s42
	s_cselect_b32 s24, s22, s29
	s_add_i32 s55, 0, 0x14000
	v_add_u32_e32 v80, s52, v111
	v_add_u32_e32 v96, s55, v111
	ds_read_b128 v[68:71], v80
	ds_read_b128 v[72:75], v80 offset:1024
	ds_read_b128 v[76:79], v80 offset:2048
	ds_read_b128 v[80:83], v80 offset:3072
	ds_read_b128 v[84:87], v96
	ds_read_b128 v[88:91], v96 offset:1024
	ds_read_b128 v[92:95], v96 offset:2048
	ds_read_b128 v[96:99], v96 offset:3072
	ds_read_b128 v[100:103], v112
	ds_read_b128 v[104:107], v112 offset:1024
	ds_read_b128 v[114:117], v112 offset:2048
	ds_read_b128 v[118:121], v112 offset:3072
	ds_read_b128 v[122:125], v112 offset:4096
	ds_read_b128 v[126:129], v112 offset:5120
	ds_read_b128 v[130:133], v112 offset:6144
	ds_read_b128 v[134:137], v112 offset:7168
	s_waitcnt lgkmcnt(0)
	s_setprio 1
	s_barrier
	v_mfma_scale_f32_16x16x128_f8f6f4 v[64:67], v[68:75], v[100:107], v[64:67], v110, v110 op_sel_hi:[0,0,0]
	v_mfma_scale_f32_16x16x128_f8f6f4 v[60:63], v[76:83], v[100:107], v[60:63], v110, v110 op_sel_hi:[0,0,0]
	v_mfma_scale_f32_16x16x128_f8f6f4 v[48:51], v[68:75], v[114:121], v[48:51], v110, v110 op_sel_hi:[0,0,0]
	v_mfma_scale_f32_16x16x128_f8f6f4 v[44:47], v[76:83], v[114:121], v[44:47], v110, v110 op_sel_hi:[0,0,0]
	v_mfma_scale_f32_16x16x128_f8f6f4 v[30:33], v[68:75], v[122:129], v[30:33], v110, v110 op_sel_hi:[0,0,0]
	v_mfma_scale_f32_16x16x128_f8f6f4 v[26:29], v[76:83], v[122:129], v[26:29], v110, v110 op_sel_hi:[0,0,0]
	v_mfma_scale_f32_16x16x128_f8f6f4 v[14:17], v[68:75], v[130:137], v[14:17], v110, v110 op_sel_hi:[0,0,0]
	v_mfma_scale_f32_16x16x128_f8f6f4 v[10:13], v[76:83], v[130:137], v[10:13], v110, v110 op_sel_hi:[0,0,0]
	v_mfma_scale_f32_16x16x128_f8f6f4 v[56:59], v[84:91], v[100:107], v[56:59], v110, v110 op_sel_hi:[0,0,0]
	v_mfma_scale_f32_16x16x128_f8f6f4 v[52:55], v[92:99], v[100:107], v[52:55], v110, v110 op_sel_hi:[0,0,0]
	v_mfma_scale_f32_16x16x128_f8f6f4 v[40:43], v[84:91], v[114:121], v[40:43], v110, v110 op_sel_hi:[0,0,0]
	v_mfma_scale_f32_16x16x128_f8f6f4 v[36:39], v[92:99], v[114:121], v[36:39], v110, v110 op_sel_hi:[0,0,0]
	v_mfma_scale_f32_16x16x128_f8f6f4 v[22:25], v[84:91], v[122:129], v[22:25], v110, v110 op_sel_hi:[0,0,0]
	v_mfma_scale_f32_16x16x128_f8f6f4 v[18:21], v[92:99], v[122:129], v[18:21], v110, v110 op_sel_hi:[0,0,0]
	v_mfma_scale_f32_16x16x128_f8f6f4 v[6:9], v[84:91], v[130:137], v[6:9], v110, v110 op_sel_hi:[0,0,0]
	v_mfma_scale_f32_16x16x128_f8f6f4 v[2:5], v[92:99], v[130:137], v[2:5], v110, v110 op_sel_hi:[0,0,0]
	s_waitcnt vmcnt(0)
	s_barrier
	s_setprio 0
	s_add_i32 s52, s52, s30
	v_lshl_add_u64 v[108:109], s[24:25], 0, v[34:35]
	s_mov_b32 m0, s52
	v_lshl_add_u64 v[138:139], s[24:25], 0, v[168:169]
	global_load_lds_dwordx4 v[108:109], off
	s_add_i32 m0, s52, 0x2000
	s_add_u32 s60, s24, 0xb0000
	s_addc_u32 s61, s25, 0
	s_add_i32 s52, s55, s30
	global_load_lds_dwordx4 v[138:139], off
	v_lshl_add_u64 v[68:69], s[60:61], 0, v[34:35]
	s_mov_b32 m0, s52
	v_lshl_add_u64 v[140:141], s[26:27], 0, v[164:165]
	global_load_lds_dwordx4 v[68:69], off
	v_lshl_add_u64 v[68:69], s[60:61], 0, v[168:169]
	s_add_i32 m0, s52, 0x2000
	v_lshl_add_u64 v[142:143], s[26:27], 0, v[166:167]
	global_load_lds_dwordx4 v[68:69], off
	s_mov_b32 m0, s31
	s_nop 0
	global_load_lds_dwordx4 v[140:141], off
	s_mov_b32 m0, s38
	s_nop 0
	global_load_lds_dwordx4 v[142:143], off
	s_barrier
	s_add_i32 s26, 0, 0x18000
	s_add_i32 s27, 0, 0x1c000
	v_add_u32_e32 v80, s26, v111
	v_add_u32_e32 v96, s27, v111
	ds_read_b128 v[68:71], v80
	ds_read_b128 v[72:75], v80 offset:1024
	ds_read_b128 v[76:79], v80 offset:2048
	ds_read_b128 v[80:83], v80 offset:3072
	ds_read_b128 v[84:87], v96
	ds_read_b128 v[88:91], v96 offset:1024
	ds_read_b128 v[92:95], v96 offset:2048
	ds_read_b128 v[96:99], v96 offset:3072
	ds_read_b128 v[100:103], v112 offset:32768
	ds_read_b128 v[104:107], v112 offset:33792
	ds_read_b128 v[114:117], v112 offset:34816
	ds_read_b128 v[118:121], v112 offset:35840
	ds_read_b128 v[122:125], v112 offset:36864
	ds_read_b128 v[126:129], v112 offset:37888
	ds_read_b128 v[130:133], v112 offset:38912
	ds_read_b128 v[134:137], v112 offset:39936
	s_waitcnt lgkmcnt(0)
	s_setprio 1
	s_barrier
	v_mfma_scale_f32_16x16x128_f8f6f4 v[64:67], v[68:75], v[100:107], v[64:67], v110, v110 op_sel_hi:[0,0,0]
	v_mfma_scale_f32_16x16x128_f8f6f4 v[60:63], v[76:83], v[100:107], v[60:63], v110, v110 op_sel_hi:[0,0,0]
	v_mfma_scale_f32_16x16x128_f8f6f4 v[48:51], v[68:75], v[114:121], v[48:51], v110, v110 op_sel_hi:[0,0,0]
	v_mfma_scale_f32_16x16x128_f8f6f4 v[44:47], v[76:83], v[114:121], v[44:47], v110, v110 op_sel_hi:[0,0,0]
	v_mfma_scale_f32_16x16x128_f8f6f4 v[30:33], v[68:75], v[122:129], v[30:33], v110, v110 op_sel_hi:[0,0,0]
	v_mfma_scale_f32_16x16x128_f8f6f4 v[26:29], v[76:83], v[122:129], v[26:29], v110, v110 op_sel_hi:[0,0,0]
	v_mfma_scale_f32_16x16x128_f8f6f4 v[14:17], v[68:75], v[130:137], v[14:17], v110, v110 op_sel_hi:[0,0,0]
	v_mfma_scale_f32_16x16x128_f8f6f4 v[10:13], v[76:83], v[130:137], v[10:13], v110, v110 op_sel_hi:[0,0,0]
	v_mfma_scale_f32_16x16x128_f8f6f4 v[56:59], v[84:91], v[100:107], v[56:59], v110, v110 op_sel_hi:[0,0,0]
	v_mfma_scale_f32_16x16x128_f8f6f4 v[52:55], v[92:99], v[100:107], v[52:55], v110, v110 op_sel_hi:[0,0,0]
	v_mfma_scale_f32_16x16x128_f8f6f4 v[40:43], v[84:91], v[114:121], v[40:43], v110, v110 op_sel_hi:[0,0,0]
	v_mfma_scale_f32_16x16x128_f8f6f4 v[36:39], v[92:99], v[114:121], v[36:39], v110, v110 op_sel_hi:[0,0,0]
	v_mfma_scale_f32_16x16x128_f8f6f4 v[22:25], v[84:91], v[122:129], v[22:25], v110, v110 op_sel_hi:[0,0,0]
	v_mfma_scale_f32_16x16x128_f8f6f4 v[18:21], v[92:99], v[122:129], v[18:21], v110, v110 op_sel_hi:[0,0,0]
	v_mfma_scale_f32_16x16x128_f8f6f4 v[6:9], v[84:91], v[130:137], v[6:9], v110, v110 op_sel_hi:[0,0,0]
	v_mfma_scale_f32_16x16x128_f8f6f4 v[2:5], v[92:99], v[130:137], v[2:5], v110, v110 op_sel_hi:[0,0,0]
	s_waitcnt vmcnt(0)
	s_barrier
	s_setprio 0
	s_add_i32 s26, s26, s30
	v_lshl_add_u64 v[68:69], v[108:109], 0, s[18:19]
	s_mov_b32 m0, s26
	s_nop 0
	global_load_lds_dwordx4 v[68:69], off
	s_add_i32 m0, s26, 0x2000
	s_add_u32 s24, s24, 0xb0080
	v_lshl_add_u64 v[68:69], v[138:139], 0, s[18:19]
	s_addc_u32 s25, s25, 0
	s_add_i32 s26, s27, s30
	global_load_lds_dwordx4 v[68:69], off
	v_lshl_add_u64 v[68:69], s[24:25], 0, v[34:35]
	s_mov_b32 m0, s26
	s_nop 0
	global_load_lds_dwordx4 v[68:69], off
	v_lshl_add_u64 v[68:69], s[24:25], 0, v[168:169]
	s_add_i32 m0, s26, 0x2000
	s_nop 0
	global_load_lds_dwordx4 v[68:69], off
	v_lshl_add_u64 v[68:69], v[140:141], 0, s[18:19]
	s_mov_b32 m0, s39
	s_nop 0
	global_load_lds_dwordx4 v[68:69], off
	v_lshl_add_u64 v[68:69], v[142:143], 0, s[18:19]
	s_mov_b32 m0, s44
	s_nop 0
	global_load_lds_dwordx4 v[68:69], off
	s_barrier
	s_add_i32 s43, s43, 2
	s_add_u32 s11, s11, 0x100
	s_addc_u32 s13, s13, 0
	s_add_u32 s29, s29, 0x100
	s_addc_u32 s42, s42, 0
	s_cmp_gt_u32 s43, 41
	s_cbranch_scc0 .LBB0_502
	s_and_b64 vcc, exec, s[16:17]
	s_cbranch_vccz .LBB0_505
	s_barrier

.LBB0_586:
	s_add_i32 s52, 0, 0x10000
	s_cmpk_eq_i32 s29, 0x54
	s_cselect_b32 s43, s21, s13
	s_cselect_b32 s42, s20, s11
	s_cselect_b32 s25, s23, s27
	s_cselect_b32 s24, s22, s26
	s_add_i32 s55, 0, 0x14000
	v_add_u32_e32 v72, s52, v110
	v_add_u32_e32 v96, s55, v110
	ds_read_b128 v[56:59], v72
	ds_read_b128 v[64:67], v72 offset:1024
	ds_read_b128 v[68:71], v72 offset:2048
	ds_read_b128 v[72:75], v72 offset:3072
	ds_read_b128 v[76:79], v96
	ds_read_b128 v[84:87], v96 offset:1024
	ds_read_b128 v[92:95], v96 offset:2048
	ds_read_b128 v[96:99], v96 offset:3072
	ds_read_b128 v[100:103], v111
	ds_read_b128 v[104:107], v111 offset:1024
	ds_read_b128 v[112:115], v111 offset:2048
	ds_read_b128 v[116:119], v111 offset:3072
	ds_read_b128 v[120:123], v111 offset:4096
	ds_read_b128 v[124:127], v111 offset:5120
	ds_read_b128 v[128:131], v111 offset:6144
	ds_read_b128 v[132:135], v111 offset:7168
	s_waitcnt lgkmcnt(0)
	s_setprio 1
	s_barrier
	v_mfma_f32_16x16x32_bf16 v[88:91], v[56:59], v[100:103], v[88:91]
	v_mfma_f32_16x16x32_bf16 v[88:91], v[64:67], v[104:107], v[88:91]
	v_mfma_f32_16x16x32_bf16 v[80:83], v[68:71], v[100:103], v[80:83]
	v_mfma_f32_16x16x32_bf16 v[80:83], v[72:75], v[104:107], v[80:83]
	v_mfma_f32_16x16x32_bf16 v[48:51], v[56:59], v[112:115], v[48:51]
	v_mfma_f32_16x16x32_bf16 v[48:51], v[64:67], v[116:119], v[48:51]
	v_mfma_f32_16x16x32_bf16 v[44:47], v[68:71], v[112:115], v[44:47]
	v_mfma_f32_16x16x32_bf16 v[44:47], v[72:75], v[116:119], v[44:47]
	v_mfma_f32_16x16x32_bf16 v[30:33], v[56:59], v[120:123], v[30:33]
	v_mfma_f32_16x16x32_bf16 v[30:33], v[64:67], v[124:127], v[30:33]
	v_mfma_f32_16x16x32_bf16 v[26:29], v[68:71], v[120:123], v[26:29]
	v_mfma_f32_16x16x32_bf16 v[26:29], v[72:75], v[124:127], v[26:29]
	v_mfma_f32_16x16x32_bf16 v[14:17], v[56:59], v[128:131], v[14:17]
	v_mfma_f32_16x16x32_bf16 v[14:17], v[64:67], v[132:135], v[14:17]
	v_mfma_f32_16x16x32_bf16 v[10:13], v[68:71], v[128:131], v[10:13]
	v_mfma_f32_16x16x32_bf16 v[10:13], v[72:75], v[132:135], v[10:13]
	v_mfma_f32_16x16x32_bf16 v[52:55], v[92:95], v[100:103], v[52:55]
	v_mfma_f32_16x16x32_bf16 v[52:55], v[96:99], v[104:107], v[52:55]
	v_mfma_f32_16x16x32_bf16 v[40:43], v[76:79], v[112:115], v[40:43]
	v_mfma_f32_16x16x32_bf16 v[40:43], v[84:87], v[116:119], v[40:43]
	v_mfma_f32_16x16x32_bf16 v[36:39], v[92:95], v[112:115], v[36:39]
	v_mfma_f32_16x16x32_bf16 v[36:39], v[96:99], v[116:119], v[36:39]
	v_mfma_f32_16x16x32_bf16 v[22:25], v[76:79], v[120:123], v[22:25]
	v_mfma_f32_16x16x32_bf16 v[22:25], v[84:87], v[124:127], v[22:25]
	v_mfma_f32_16x16x32_bf16 v[18:21], v[92:95], v[120:123], v[18:21]
	v_mfma_f32_16x16x32_bf16 v[18:21], v[96:99], v[124:127], v[18:21]
	v_mfma_f32_16x16x32_bf16 v[6:9], v[76:79], v[128:131], v[6:9]
	v_mfma_f32_16x16x32_bf16 v[6:9], v[84:87], v[132:135], v[6:9]
	v_mfma_f32_16x16x32_bf16 v[2:5], v[92:95], v[128:131], v[2:5]
	v_mfma_f32_16x16x32_bf16 v[2:5], v[96:99], v[132:135], v[2:5]
	v_mfma_f32_16x16x32_bf16 v[56:59], v[76:79], v[100:103], v[60:63]
	v_mfma_f32_16x16x32_bf16 v[56:59], v[84:87], v[104:107], v[56:59]
	s_waitcnt vmcnt(0)
	s_barrier
	s_setprio 0
	s_add_i32 s52, s52, s30
	v_lshl_add_u64 v[108:109], s[24:25], 0, v[34:35]
	s_mov_b32 m0, s52
	v_lshl_add_u64 v[136:137], s[24:25], 0, v[164:165]
	global_load_lds_dwordx4 v[108:109], off
	s_add_i32 m0, s52, 0x2000
	s_add_u32 s60, s24, 0x160000
	s_addc_u32 s61, s25, 0
	s_add_i32 s52, s55, s30
	global_load_lds_dwordx4 v[136:137], off
	v_lshl_add_u64 v[60:61], s[60:61], 0, v[34:35]
	s_mov_b32 m0, s52
	v_lshl_add_u64 v[138:139], s[42:43], 0, v[160:161]
	global_load_lds_dwordx4 v[60:61], off
	v_lshl_add_u64 v[60:61], s[60:61], 0, v[164:165]
	s_add_i32 m0, s52, 0x2000
	v_lshl_add_u64 v[140:141], s[42:43], 0, v[162:163]
	global_load_lds_dwordx4 v[60:61], off
	s_mov_b32 m0, s31
	s_nop 0
	global_load_lds_dwordx4 v[138:139], off
	s_mov_b32 m0, s38
	s_nop 0
	global_load_lds_dwordx4 v[140:141], off
	s_barrier
	s_add_i32 s42, 0, 0x18000
	s_add_i32 s43, 0, 0x1c000
	v_add_u32_e32 v72, s42, v110
	v_add_u32_e32 v96, s43, v110
	ds_read_b128 v[60:63], v72
	ds_read_b128 v[64:67], v72 offset:1024
	ds_read_b128 v[68:71], v72 offset:2048
	ds_read_b128 v[72:75], v72 offset:3072
	ds_read_b128 v[76:79], v96
	ds_read_b128 v[84:87], v96 offset:1024
	ds_read_b128 v[92:95], v96 offset:2048
	ds_read_b128 v[96:99], v96 offset:3072
	ds_read_b128 v[100:103], v111 offset:32768
	ds_read_b128 v[104:107], v111 offset:33792
	ds_read_b128 v[112:115], v111 offset:34816
	ds_read_b128 v[116:119], v111 offset:35840
	ds_read_b128 v[120:123], v111 offset:36864
	ds_read_b128 v[124:127], v111 offset:37888
	ds_read_b128 v[128:131], v111 offset:38912
	ds_read_b128 v[132:135], v111 offset:39936
	s_waitcnt lgkmcnt(0)
	s_setprio 1
	s_barrier
	v_mfma_f32_16x16x32_bf16 v[88:91], v[60:63], v[100:103], v[88:91]
	v_mfma_f32_16x16x32_bf16 v[88:91], v[64:67], v[104:107], v[88:91]
	v_mfma_f32_16x16x32_bf16 v[80:83], v[68:71], v[100:103], v[80:83]
	v_mfma_f32_16x16x32_bf16 v[80:83], v[72:75], v[104:107], v[80:83]
	v_mfma_f32_16x16x32_bf16 v[48:51], v[60:63], v[112:115], v[48:51]
	v_mfma_f32_16x16x32_bf16 v[48:51], v[64:67], v[116:119], v[48:51]
	v_mfma_f32_16x16x32_bf16 v[44:47], v[68:71], v[112:115], v[44:47]
	v_mfma_f32_16x16x32_bf16 v[44:47], v[72:75], v[116:119], v[44:47]
	v_mfma_f32_16x16x32_bf16 v[30:33], v[60:63], v[120:123], v[30:33]
	v_mfma_f32_16x16x32_bf16 v[30:33], v[64:67], v[124:127], v[30:33]
	v_mfma_f32_16x16x32_bf16 v[26:29], v[68:71], v[120:123], v[26:29]
	v_mfma_f32_16x16x32_bf16 v[26:29], v[72:75], v[124:127], v[26:29]
	v_mfma_f32_16x16x32_bf16 v[14:17], v[60:63], v[128:131], v[14:17]
	v_mfma_f32_16x16x32_bf16 v[14:17], v[64:67], v[132:135], v[14:17]
	v_mfma_f32_16x16x32_bf16 v[10:13], v[68:71], v[128:131], v[10:13]
	v_mfma_f32_16x16x32_bf16 v[10:13], v[72:75], v[132:135], v[10:13]
	v_mfma_f32_16x16x32_bf16 v[56:59], v[76:79], v[100:103], v[56:59]
	v_mfma_f32_16x16x32_bf16 v[60:63], v[84:87], v[104:107], v[56:59]
	v_mfma_f32_16x16x32_bf16 v[52:55], v[92:95], v[100:103], v[52:55]
	v_mfma_f32_16x16x32_bf16 v[52:55], v[96:99], v[104:107], v[52:55]
	v_mfma_f32_16x16x32_bf16 v[40:43], v[76:79], v[112:115], v[40:43]
	v_mfma_f32_16x16x32_bf16 v[40:43], v[84:87], v[116:119], v[40:43]
	v_mfma_f32_16x16x32_bf16 v[36:39], v[92:95], v[112:115], v[36:39]
	v_mfma_f32_16x16x32_bf16 v[36:39], v[96:99], v[116:119], v[36:39]
	v_mfma_f32_16x16x32_bf16 v[22:25], v[76:79], v[120:123], v[22:25]
	v_mfma_f32_16x16x32_bf16 v[22:25], v[84:87], v[124:127], v[22:25]
	v_mfma_f32_16x16x32_bf16 v[18:21], v[92:95], v[120:123], v[18:21]
	v_mfma_f32_16x16x32_bf16 v[18:21], v[96:99], v[124:127], v[18:21]
	v_mfma_f32_16x16x32_bf16 v[6:9], v[76:79], v[128:131], v[6:9]
	v_mfma_f32_16x16x32_bf16 v[6:9], v[84:87], v[132:135], v[6:9]
	v_mfma_f32_16x16x32_bf16 v[2:5], v[92:95], v[128:131], v[2:5]
	v_mfma_f32_16x16x32_bf16 v[2:5], v[96:99], v[132:135], v[2:5]
	s_waitcnt vmcnt(0)
	s_barrier
	s_setprio 0
	s_add_i32 s42, s42, s30
	v_lshl_add_u64 v[56:57], v[108:109], 0, s[18:19]
	s_mov_b32 m0, s42
	s_nop 0
	global_load_lds_dwordx4 v[56:57], off
	s_add_i32 m0, s42, 0x2000
	s_add_u32 s24, s24, 0x160080
	v_lshl_add_u64 v[56:57], v[136:137], 0, s[18:19]
	s_addc_u32 s25, s25, 0
	s_add_i32 s42, s43, s30
	global_load_lds_dwordx4 v[56:57], off
	v_lshl_add_u64 v[56:57], s[24:25], 0, v[34:35]
	s_mov_b32 m0, s42
	s_nop 0
	global_load_lds_dwordx4 v[56:57], off
	v_lshl_add_u64 v[56:57], s[24:25], 0, v[164:165]
	s_add_i32 m0, s42, 0x2000
	s_nop 0
	global_load_lds_dwordx4 v[56:57], off
	v_lshl_add_u64 v[56:57], v[138:139], 0, s[18:19]
	s_mov_b32 m0, s39
	s_nop 0
	global_load_lds_dwordx4 v[56:57], off
	v_lshl_add_u64 v[56:57], v[140:141], 0, s[18:19]
	s_mov_b32 m0, s44
	s_nop 0
	global_load_lds_dwordx4 v[56:57], off
	s_barrier
	s_add_i32 s29, s29, 2
	s_add_u32 s11, s11, 0x100
	s_addc_u32 s13, s13, 0
	s_add_u32 s26, s26, 0x100
	s_addc_u32 s27, s27, 0
	s_cmpk_gt_u32 s29, 0x55
	s_cbranch_scc0 .LBB0_586
	s_and_b64 vcc, exec, s[16:17]
	s_cbranch_vccz .LBB0_589
	s_barrier

.LBB0_891:
	v_mfma_f32_16x16x32_bf16 v[64:67], v[100:103], v[124:127], v[64:67]
	v_mfma_f32_16x16x32_bf16 v[64:67], v[104:107], v[128:131], v[64:67]
	v_mfma_f32_16x16x32_bf16 v[60:63], v[108:111], v[124:127], v[60:63]
	v_mfma_f32_16x16x32_bf16 v[60:63], v[112:115], v[128:131], v[60:63]
	v_mfma_f32_16x16x32_bf16 v[48:51], v[100:103], v[116:119], v[48:51]
	v_mfma_f32_16x16x32_bf16 v[48:51], v[104:107], v[120:123], v[48:51]
	v_mfma_f32_16x16x32_bf16 v[44:47], v[108:111], v[116:119], v[44:47]
	v_mfma_f32_16x16x32_bf16 v[44:47], v[112:115], v[120:123], v[44:47]
	v_mfma_f32_16x16x32_bf16 v[30:33], v[100:103], v[92:95], v[30:33]
	v_mfma_f32_16x16x32_bf16 v[30:33], v[104:107], v[96:99], v[30:33]
	v_mfma_f32_16x16x32_bf16 v[26:29], v[108:111], v[92:95], v[26:29]
	v_mfma_f32_16x16x32_bf16 v[26:29], v[112:115], v[96:99], v[26:29]
	v_mfma_f32_16x16x32_bf16 v[14:17], v[100:103], v[84:87], v[14:17]
	v_mfma_f32_16x16x32_bf16 v[14:17], v[104:107], v[88:91], v[14:17]
	v_mfma_f32_16x16x32_bf16 v[10:13], v[108:111], v[84:87], v[10:13]
	v_mfma_f32_16x16x32_bf16 v[10:13], v[112:115], v[88:91], v[10:13]
	v_mfma_f32_16x16x32_bf16 v[56:59], v[68:71], v[124:127], v[56:59]
	v_mfma_f32_16x16x32_bf16 v[56:59], v[72:75], v[128:131], v[56:59]
	v_mfma_f32_16x16x32_bf16 v[52:55], v[76:79], v[124:127], v[52:55]
	v_mfma_f32_16x16x32_bf16 v[52:55], v[80:83], v[128:131], v[52:55]
	v_mfma_f32_16x16x32_bf16 v[40:43], v[68:71], v[116:119], v[40:43]
	v_mfma_f32_16x16x32_bf16 v[40:43], v[72:75], v[120:123], v[40:43]
	v_mfma_f32_16x16x32_bf16 v[36:39], v[76:79], v[116:119], v[36:39]
	v_mfma_f32_16x16x32_bf16 v[36:39], v[80:83], v[120:123], v[36:39]
	v_mfma_f32_16x16x32_bf16 v[22:25], v[68:71], v[92:95], v[22:25]
	v_mfma_f32_16x16x32_bf16 v[22:25], v[72:75], v[96:99], v[22:25]
	v_mfma_f32_16x16x32_bf16 v[18:21], v[76:79], v[92:95], v[18:21]
	v_mfma_f32_16x16x32_bf16 v[18:21], v[80:83], v[96:99], v[18:21]
	v_mfma_f32_16x16x32_bf16 v[6:9], v[68:71], v[84:87], v[6:9]
	v_mfma_f32_16x16x32_bf16 v[6:9], v[72:75], v[88:91], v[6:9]
	v_mfma_f32_16x16x32_bf16 v[2:5], v[76:79], v[84:87], v[2:5]
	v_mfma_f32_16x16x32_bf16 v[2:5], v[80:83], v[88:91], v[2:5]
	s_waitcnt vmcnt(0)
	s_barrier
	s_setprio 0
	s_mov_b32 m0, s52
	v_lshl_add_u64 v[138:139], s[34:35], 0, v[208:209]
	s_add_u32 s70, s34, 0x80000
	global_load_lds_dwordx4 v[138:139], off
	v_lshl_add_u64 v[140:141], s[34:35], 0, v[212:213]
	s_mov_b32 m0, s54
	s_addc_u32 s71, s35, 0
	global_load_lds_dwordx4 v[140:141], off
	v_lshl_add_u64 v[68:69], s[70:71], 0, v[208:209]
	s_mov_b32 m0, s55
	v_lshl_add_u64 v[142:143], s[68:69], 0, v[206:207]
	global_load_lds_dwordx4 v[68:69], off
	v_lshl_add_u64 v[68:69], s[70:71], 0, v[212:213]
	s_mov_b32 m0, s59
	v_lshl_add_u64 v[144:145], s[68:69], 0, v[210:211]
	global_load_lds_dwordx4 v[68:69], off
	s_mov_b32 m0, s47
	s_nop 0
	global_load_lds_dwordx4 v[142:143], off
	s_mov_b32 m0, s60
	s_nop 0
	global_load_lds_dwordx4 v[144:145], off
	s_barrier
	s_add_i32 s67, 0, 0x18000
	v_add_u32_e32 v34, s67, v136
	s_add_i32 s68, 0, 0x1c000
	ds_read_b128 v[68:71], v34
	ds_read_b128 v[72:75], v34 offset:1024
	ds_read_b128 v[76:79], v34 offset:2048
	ds_read_b128 v[80:83], v34 offset:3072
	v_add_u32_e32 v34, s68, v136
	ds_read_b128 v[84:87], v34
	ds_read_b128 v[88:91], v34 offset:1024
	ds_read_b128 v[92:95], v34 offset:2048
	ds_read_b128 v[96:99], v34 offset:3072
	ds_read_b128 v[100:103], v137 offset:32768
	ds_read_b128 v[104:107], v137 offset:33792
	ds_read_b128 v[108:111], v137 offset:34816
	ds_read_b128 v[112:115], v137 offset:35840
	ds_read_b128 v[116:119], v137 offset:36864
	ds_read_b128 v[120:123], v137 offset:37888
	ds_read_b128 v[124:127], v137 offset:38912
	ds_read_b128 v[128:131], v137 offset:39936
	s_waitcnt lgkmcnt(0)
	s_setprio 1
	s_barrier
	v_mfma_f32_16x16x32_bf16 v[64:67], v[68:71], v[100:103], v[64:67]
	v_mfma_f32_16x16x32_bf16 v[64:67], v[72:75], v[104:107], v[64:67]
	v_mfma_f32_16x16x32_bf16 v[60:63], v[76:79], v[100:103], v[60:63]
	v_mfma_f32_16x16x32_bf16 v[60:63], v[80:83], v[104:107], v[60:63]
	v_mfma_f32_16x16x32_bf16 v[48:51], v[68:71], v[108:111], v[48:51]
	v_mfma_f32_16x16x32_bf16 v[48:51], v[72:75], v[112:115], v[48:51]
	v_mfma_f32_16x16x32_bf16 v[44:47], v[76:79], v[108:111], v[44:47]
	v_mfma_f32_16x16x32_bf16 v[44:47], v[80:83], v[112:115], v[44:47]
	v_mfma_f32_16x16x32_bf16 v[30:33], v[68:71], v[116:119], v[30:33]
	v_mfma_f32_16x16x32_bf16 v[30:33], v[72:75], v[120:123], v[30:33]
	v_mfma_f32_16x16x32_bf16 v[26:29], v[76:79], v[116:119], v[26:29]
	v_mfma_f32_16x16x32_bf16 v[26:29], v[80:83], v[120:123], v[26:29]
	v_mfma_f32_16x16x32_bf16 v[14:17], v[68:71], v[124:127], v[14:17]
	v_mfma_f32_16x16x32_bf16 v[14:17], v[72:75], v[128:131], v[14:17]
	v_mfma_f32_16x16x32_bf16 v[10:13], v[76:79], v[124:127], v[10:13]
	v_mfma_f32_16x16x32_bf16 v[10:13], v[80:83], v[128:131], v[10:13]
	v_mfma_f32_16x16x32_bf16 v[56:59], v[84:87], v[100:103], v[56:59]
	v_mfma_f32_16x16x32_bf16 v[56:59], v[88:91], v[104:107], v[56:59]
	v_mfma_f32_16x16x32_bf16 v[52:55], v[92:95], v[100:103], v[52:55]
	v_mfma_f32_16x16x32_bf16 v[52:55], v[96:99], v[104:107], v[52:55]
	v_mfma_f32_16x16x32_bf16 v[40:43], v[84:87], v[108:111], v[40:43]
	v_mfma_f32_16x16x32_bf16 v[40:43], v[88:91], v[112:115], v[40:43]
	v_mfma_f32_16x16x32_bf16 v[36:39], v[92:95], v[108:111], v[36:39]
	v_mfma_f32_16x16x32_bf16 v[36:39], v[96:99], v[112:115], v[36:39]
	v_mfma_f32_16x16x32_bf16 v[22:25], v[84:87], v[116:119], v[22:25]
	v_mfma_f32_16x16x32_bf16 v[22:25], v[88:91], v[120:123], v[22:25]
	v_mfma_f32_16x16x32_bf16 v[18:21], v[92:95], v[116:119], v[18:21]
	v_mfma_f32_16x16x32_bf16 v[18:21], v[96:99], v[120:123], v[18:21]
	v_mfma_f32_16x16x32_bf16 v[6:9], v[84:87], v[124:127], v[6:9]
	v_mfma_f32_16x16x32_bf16 v[6:9], v[88:91], v[128:131], v[6:9]
	v_mfma_f32_16x16x32_bf16 v[2:5], v[92:95], v[124:127], v[2:5]
	v_mfma_f32_16x16x32_bf16 v[2:5], v[96:99], v[128:131], v[2:5]
	s_waitcnt vmcnt(0)
	s_barrier
	s_setprio 0
	s_add_i32 s67, s67, s46
	v_lshl_add_u64 v[68:69], v[138:139], 0, s[18:19]
	s_mov_b32 m0, s67
	s_nop 0
	global_load_lds_dwordx4 v[68:69], off
	s_add_i32 m0, s67, 0x2000
	s_add_u32 s34, s34, 0x80080
	v_lshl_add_u64 v[68:69], v[140:141], 0, s[18:19]
	s_addc_u32 s35, s35, 0
	s_add_i32 s67, s68, s46
	global_load_lds_dwordx4 v[68:69], off
	v_lshl_add_u64 v[68:69], s[34:35], 0, v[208:209]
	s_mov_b32 m0, s67
	s_nop 0
	global_load_lds_dwordx4 v[68:69], off
	v_lshl_add_u64 v[68:69], s[34:35], 0, v[212:213]
	s_add_i32 m0, s67, 0x2000
	s_nop 0
	global_load_lds_dwordx4 v[68:69], off
	v_lshl_add_u64 v[68:69], v[142:143], 0, s[18:19]
	s_mov_b32 m0, s61
	s_nop 0
	global_load_lds_dwordx4 v[68:69], off
	v_lshl_add_u64 v[68:69], v[144:145], 0, s[18:19]
	s_mov_b32 m0, s62
	s_nop 0
	global_load_lds_dwordx4 v[68:69], off
	s_barrier
	s_add_i32 s66, s66, 2
	s_add_u32 s29, s29, 0x100
	s_addc_u32 s36, s36, 0
	s_add_u32 s37, s37, 0x100
	s_addc_u32 s43, s43, 0
	s_cmp_gt_u32 s66, 29
	s_cbranch_scc1 .LBB0_894
.LBB0_892:
	v_add_u32_e32 v34, 0, v136
	v_add_u32_e32 v68, 0x10000, v34
	v_add_u32_e32 v34, 0x14000, v34
	ds_read_b128 v[100:103], v68
	ds_read_b128 v[104:107], v68 offset:1024
	ds_read_b128 v[108:111], v68 offset:2048
	ds_read_b128 v[112:115], v68 offset:3072
	ds_read_b128 v[68:71], v34
	ds_read_b128 v[72:75], v34 offset:1024
	ds_read_b128 v[76:79], v34 offset:2048
	ds_read_b128 v[80:83], v34 offset:3072
	ds_read_b128 v[124:127], v137
	ds_read_b128 v[128:131], v137 offset:1024
	ds_read_b128 v[116:119], v137 offset:2048
	ds_read_b128 v[120:123], v137 offset:3072
	ds_read_b128 v[92:95], v137 offset:4096
	ds_read_b128 v[96:99], v137 offset:5120
	ds_read_b128 v[84:87], v137 offset:6144
	ds_read_b128 v[88:91], v137 offset:7168
	s_waitcnt lgkmcnt(0)
	s_cmp_lg_u32 s66, -2
	s_cmp_eq_u32 s66, 28
	s_cselect_b32 s69, s21, s36
	s_cselect_b32 s68, s27, s29
	s_cselect_b32 s35, s17, s43
	s_cselect_b32 s34, s42, s37
	s_cmp_lg_u32 s66, -2
	s_setprio 1
	s_barrier
	s_cbranch_scc1 .LBB0_891
	s_add_i32 m0, s47, 0x21200
	s_nop 0
	global_load_lds_dwordx4 v[134:135], off
	s_branch .LBB0_891

.LBB0_1183:
	s_add_u32 s13, s22, s30
	s_addc_u32 s28, s23, s31
	s_add_u32 s13, s13, 0x100
	s_addc_u32 s34, s28, 0
	s_and_b64 s[28:29], s[26:27], exec
	s_cselect_b32 s28, s14, s13
	s_cselect_b32 s29, s15, s34
	s_add_u32 s13, s20, s30
	s_addc_u32 s30, s21, s31
	s_add_u32 s13, s13, 0x100
	s_addc_u32 s30, s30, 0
	s_add_i32 s46, 0, 0x10000
	s_and_b64 s[26:27], s[26:27], exec
	s_cselect_b32 s31, s17, s30
	s_cselect_b32 s30, s16, s13
	s_add_i32 s13, s46, s36
	v_add_u32_e32 v34, s46, v40
	s_add_i32 s47, s13, 0x2000
	ds_read_b128 v[36:39], v34
	ds_read_b128 v[42:45], v34 offset:1024
	ds_read_b128 v[46:49], v34 offset:2048
	ds_read_b128 v[50:53], v34 offset:3072
	s_add_u32 s34, s30, 0x10000
	s_addc_u32 s35, s31, 0
	s_add_i32 s55, 0, 0x18000
	s_add_i32 s72, s55, s36
	s_add_i32 s46, s72, 0x2000
	s_add_u32 s26, s30, 0x10080
	s_addc_u32 s27, s31, 0
	ds_read_b128 v[54:57], v41
	ds_read_b128 v[58:61], v41 offset:1024
	ds_read_b128 v[62:65], v41 offset:2048
	ds_read_b128 v[76:79], v41 offset:3072
	ds_read_b128 v[82:85], v41 offset:4096
	ds_read_b128 v[86:89], v41 offset:5120
	ds_read_b128 v[90:93], v41 offset:6144
	ds_read_b128 v[94:97], v41 offset:7168
	s_waitcnt lgkmcnt(0)
	s_setprio 1
	s_barrier
	v_mfma_f32_16x16x32_bf16 v[30:33], v[36:39], v[54:57], v[30:33]
	v_mfma_f32_16x16x32_bf16 v[30:33], v[42:45], v[58:61], v[30:33]
	v_mfma_f32_16x16x32_bf16 v[26:29], v[46:49], v[54:57], v[26:29]
	v_mfma_f32_16x16x32_bf16 v[26:29], v[50:53], v[58:61], v[26:29]
	v_mfma_f32_16x16x32_bf16 v[22:25], v[36:39], v[62:65], v[22:25]
	v_mfma_f32_16x16x32_bf16 v[22:25], v[42:45], v[76:79], v[22:25]
	v_mfma_f32_16x16x32_bf16 v[18:21], v[46:49], v[62:65], v[18:21]
	v_mfma_f32_16x16x32_bf16 v[18:21], v[50:53], v[76:79], v[18:21]
	v_mfma_f32_16x16x32_bf16 v[14:17], v[36:39], v[82:85], v[14:17]
	v_mfma_f32_16x16x32_bf16 v[14:17], v[42:45], v[86:89], v[14:17]
	v_mfma_f32_16x16x32_bf16 v[10:13], v[46:49], v[82:85], v[10:13]
	v_mfma_f32_16x16x32_bf16 v[10:13], v[50:53], v[86:89], v[10:13]
	v_mfma_f32_16x16x32_bf16 v[6:9], v[36:39], v[90:93], v[6:9]
	v_mfma_f32_16x16x32_bf16 v[6:9], v[42:45], v[94:97], v[6:9]
	v_mfma_f32_16x16x32_bf16 v[2:5], v[46:49], v[90:93], v[2:5]
	v_mfma_f32_16x16x32_bf16 v[2:5], v[50:53], v[94:97], v[2:5]
	s_waitcnt vmcnt(0)
	s_barrier
	s_setprio 0
	s_mov_b32 m0, s13
	v_lshl_add_u64 v[66:67], s[30:31], 0, v[70:71]
	global_load_lds_dwordx4 v[66:67], off
	v_lshl_add_u64 v[98:99], s[30:31], 0, v[74:75]
	s_mov_b32 m0, s47
	v_lshl_add_u64 v[36:37], s[34:35], 0, v[70:71]
	global_load_lds_dwordx4 v[98:99], off
	s_mov_b32 m0, s62
	v_lshl_add_u64 v[100:101], s[28:29], 0, v[68:69]
	global_load_lds_dwordx4 v[36:37], off
	v_lshl_add_u64 v[36:37], s[34:35], 0, v[74:75]
	s_mov_b32 m0, s63
	v_lshl_add_u64 v[102:103], s[28:29], 0, v[72:73]
	global_load_lds_dwordx4 v[36:37], off
	s_mov_b32 m0, s37
	s_nop 0
	global_load_lds_dwordx4 v[100:101], off
	s_mov_b32 m0, s64
	s_nop 0
	global_load_lds_dwordx4 v[102:103], off
	s_barrier
	v_add_u32_e32 v34, s55, v40
	ds_read_b128 v[36:39], v34
	ds_read_b128 v[42:45], v34 offset:1024
	ds_read_b128 v[46:49], v34 offset:2048
	ds_read_b128 v[50:53], v34 offset:3072
	ds_read_b128 v[54:57], v41 offset:32768
	ds_read_b128 v[58:61], v41 offset:33792
	ds_read_b128 v[62:65], v41 offset:34816
	ds_read_b128 v[76:79], v41 offset:35840
	ds_read_b128 v[82:85], v41 offset:36864
	ds_read_b128 v[86:89], v41 offset:37888
	ds_read_b128 v[90:93], v41 offset:38912
	ds_read_b128 v[94:97], v41 offset:39936
	s_waitcnt lgkmcnt(0)
	s_setprio 1
	s_barrier
	v_mfma_f32_16x16x32_bf16 v[30:33], v[36:39], v[54:57], v[30:33]
	v_mfma_f32_16x16x32_bf16 v[30:33], v[42:45], v[58:61], v[30:33]
	v_mfma_f32_16x16x32_bf16 v[26:29], v[46:49], v[54:57], v[26:29]
	v_mfma_f32_16x16x32_bf16 v[26:29], v[50:53], v[58:61], v[26:29]
	v_mfma_f32_16x16x32_bf16 v[22:25], v[36:39], v[62:65], v[22:25]
	v_mfma_f32_16x16x32_bf16 v[22:25], v[42:45], v[76:79], v[22:25]
	v_mfma_f32_16x16x32_bf16 v[18:21], v[46:49], v[62:65], v[18:21]
	v_mfma_f32_16x16x32_bf16 v[18:21], v[50:53], v[76:79], v[18:21]
	v_mfma_f32_16x16x32_bf16 v[14:17], v[36:39], v[82:85], v[14:17]
	v_mfma_f32_16x16x32_bf16 v[14:17], v[42:45], v[86:89], v[14:17]
	v_mfma_f32_16x16x32_bf16 v[10:13], v[46:49], v[82:85], v[10:13]
	v_mfma_f32_16x16x32_bf16 v[10:13], v[50:53], v[86:89], v[10:13]
	v_mfma_f32_16x16x32_bf16 v[6:9], v[36:39], v[90:93], v[6:9]
	v_mfma_f32_16x16x32_bf16 v[6:9], v[42:45], v[94:97], v[6:9]
	v_mfma_f32_16x16x32_bf16 v[2:5], v[46:49], v[90:93], v[2:5]
	v_mfma_f32_16x16x32_bf16 v[2:5], v[50:53], v[94:97], v[2:5]
	s_waitcnt vmcnt(0)
	s_barrier
	s_setprio 0
	s_mov_b32 m0, s72
	v_lshl_add_u64 v[36:37], v[66:67], 0, s[18:19]
	global_load_lds_dwordx4 v[36:37], off
	v_lshl_add_u64 v[36:37], v[98:99], 0, s[18:19]
	s_mov_b32 m0, s46
	s_nop 0
	global_load_lds_dwordx4 v[36:37], off
	v_lshl_add_u64 v[36:37], s[26:27], 0, v[70:71]
	s_mov_b32 m0, s67
	s_nop 0
	global_load_lds_dwordx4 v[36:37], off
	v_lshl_add_u64 v[36:37], s[26:27], 0, v[74:75]
	s_mov_b32 m0, s68
	s_nop 0
	global_load_lds_dwordx4 v[36:37], off
	v_lshl_add_u64 v[36:37], v[100:101], 0, s[18:19]
	s_mov_b32 m0, s65
	s_nop 0
	global_load_lds_dwordx4 v[36:37], off
	v_lshl_add_u64 v[36:37], v[102:103], 0, s[18:19]
	s_mov_b32 m0, s66
	s_nop 0
	global_load_lds_dwordx4 v[36:37], off
	s_barrier
	s_andn2_b64 vcc, exec, s[24:25]
	s_mov_b64 s[26:27], -1
	s_mov_b64 s[24:25], 0
	s_mov_b64 s[30:31], 0x100
	s_cbranch_vccz .LBB0_1183
	s_and_b64 vcc, exec, s[10:11]
	s_cbranch_vccz .LBB0_1186
	s_barrier

.LBB0_1429:
	s_add_i32 s46, 0, 0x10000
	s_cmp_eq_u32 s43, 2
	s_cselect_b32 s45, s13, s21
	s_cselect_b32 s44, s12, s20
	v_add_u32_e32 v34, s46, v74
	s_cselect_b32 s17, s15, s42
	s_cselect_b32 s16, s14, s39
	s_add_i32 s52, 0, 0x14000
	ds_read_b128 v[68:71], v34
	ds_read_b128 v[76:79], v34 offset:1024
	ds_read_b128 v[80:83], v34 offset:2048
	ds_read_b128 v[84:87], v34 offset:3072
	v_add_u32_e32 v34, s52, v74
	ds_read_b128 v[88:91], v34
	ds_read_b128 v[92:95], v34 offset:1024
	ds_read_b128 v[96:99], v34 offset:2048
	ds_read_b128 v[100:103], v34 offset:3072
	ds_read_b128 v[104:107], v75
	ds_read_b128 v[108:111], v75 offset:1024
	ds_read_b128 v[112:115], v75 offset:2048
	ds_read_b128 v[116:119], v75 offset:3072
	ds_read_b128 v[120:123], v75 offset:4096
	ds_read_b128 v[124:127], v75 offset:5120
	ds_read_b128 v[128:131], v75 offset:6144
	ds_read_b128 v[140:143], v75 offset:7168
	s_waitcnt lgkmcnt(0)
	s_setprio 1
	s_barrier
	v_mfma_f32_16x16x32_bf16 v[64:67], v[68:71], v[104:107], v[64:67]
	v_mfma_f32_16x16x32_bf16 v[64:67], v[76:79], v[108:111], v[64:67]
	v_mfma_f32_16x16x32_bf16 v[60:63], v[80:83], v[104:107], v[60:63]
	v_mfma_f32_16x16x32_bf16 v[60:63], v[84:87], v[108:111], v[60:63]
	v_mfma_f32_16x16x32_bf16 v[48:51], v[68:71], v[112:115], v[48:51]
	v_mfma_f32_16x16x32_bf16 v[48:51], v[76:79], v[116:119], v[48:51]
	v_mfma_f32_16x16x32_bf16 v[44:47], v[80:83], v[112:115], v[44:47]
	v_mfma_f32_16x16x32_bf16 v[44:47], v[84:87], v[116:119], v[44:47]
	v_mfma_f32_16x16x32_bf16 v[30:33], v[68:71], v[120:123], v[30:33]
	v_mfma_f32_16x16x32_bf16 v[30:33], v[76:79], v[124:127], v[30:33]
	v_mfma_f32_16x16x32_bf16 v[26:29], v[80:83], v[120:123], v[26:29]
	v_mfma_f32_16x16x32_bf16 v[26:29], v[84:87], v[124:127], v[26:29]
	v_mfma_f32_16x16x32_bf16 v[14:17], v[68:71], v[128:131], v[14:17]
	v_mfma_f32_16x16x32_bf16 v[14:17], v[76:79], v[140:143], v[14:17]
	v_mfma_f32_16x16x32_bf16 v[10:13], v[80:83], v[128:131], v[10:13]
	v_mfma_f32_16x16x32_bf16 v[10:13], v[84:87], v[140:143], v[10:13]
	v_mfma_f32_16x16x32_bf16 v[56:59], v[88:91], v[104:107], v[56:59]
	v_mfma_f32_16x16x32_bf16 v[56:59], v[92:95], v[108:111], v[56:59]
	v_mfma_f32_16x16x32_bf16 v[52:55], v[96:99], v[104:107], v[52:55]
	v_mfma_f32_16x16x32_bf16 v[52:55], v[100:103], v[108:111], v[52:55]
	v_mfma_f32_16x16x32_bf16 v[40:43], v[88:91], v[112:115], v[40:43]
	v_mfma_f32_16x16x32_bf16 v[40:43], v[92:95], v[116:119], v[40:43]
	v_mfma_f32_16x16x32_bf16 v[36:39], v[96:99], v[112:115], v[36:39]
	v_mfma_f32_16x16x32_bf16 v[36:39], v[100:103], v[116:119], v[36:39]
	v_mfma_f32_16x16x32_bf16 v[22:25], v[88:91], v[120:123], v[22:25]
	v_mfma_f32_16x16x32_bf16 v[22:25], v[92:95], v[124:127], v[22:25]
	v_mfma_f32_16x16x32_bf16 v[18:21], v[96:99], v[120:123], v[18:21]
	v_mfma_f32_16x16x32_bf16 v[18:21], v[100:103], v[124:127], v[18:21]
	v_mfma_f32_16x16x32_bf16 v[6:9], v[88:91], v[128:131], v[6:9]
	v_mfma_f32_16x16x32_bf16 v[6:9], v[92:95], v[140:143], v[6:9]
	v_mfma_f32_16x16x32_bf16 v[2:5], v[96:99], v[128:131], v[2:5]
	v_mfma_f32_16x16x32_bf16 v[2:5], v[100:103], v[140:143], v[2:5]
	s_waitcnt vmcnt(0)
	s_barrier
	s_setprio 0
	s_add_i32 s46, s46, s22
	v_lshl_add_u64 v[72:73], s[16:17], 0, v[134:135]
	s_mov_b32 m0, s46
	v_lshl_add_u64 v[144:145], s[16:17], 0, v[138:139]
	global_load_lds_dwordx4 v[72:73], off
	s_add_i32 m0, s46, 0x2000
	s_add_u32 s46, s16, 0x18000
	s_addc_u32 s47, s17, 0
	s_add_i32 s52, s52, s22
	global_load_lds_dwordx4 v[144:145], off
	v_lshl_add_u64 v[68:69], s[46:47], 0, v[134:135]
	s_mov_b32 m0, s52
	v_lshl_add_u64 v[146:147], s[44:45], 0, v[132:133]
	global_load_lds_dwordx4 v[68:69], off
	v_lshl_add_u64 v[68:69], s[46:47], 0, v[138:139]
	s_add_i32 m0, s52, 0x2000
	v_lshl_add_u64 v[148:149], s[44:45], 0, v[136:137]
	global_load_lds_dwordx4 v[68:69], off
	s_mov_b32 m0, s23
	s_nop 0
	global_load_lds_dwordx4 v[146:147], off
	s_mov_b32 m0, s24
	s_nop 0
	global_load_lds_dwordx4 v[148:149], off
	s_barrier
	s_add_i32 s44, 0, 0x18000
	v_add_u32_e32 v34, s44, v74
	s_add_i32 s45, 0, 0x1c000
	ds_read_b128 v[68:71], v34
	ds_read_b128 v[76:79], v34 offset:1024
	ds_read_b128 v[80:83], v34 offset:2048
	ds_read_b128 v[84:87], v34 offset:3072
	v_add_u32_e32 v34, s45, v74
	ds_read_b128 v[88:91], v34
	ds_read_b128 v[92:95], v34 offset:1024
	ds_read_b128 v[96:99], v34 offset:2048
	ds_read_b128 v[100:103], v34 offset:3072
	ds_read_b128 v[104:107], v75 offset:32768
	ds_read_b128 v[108:111], v75 offset:33792
	ds_read_b128 v[112:115], v75 offset:34816
	ds_read_b128 v[116:119], v75 offset:35840
	ds_read_b128 v[120:123], v75 offset:36864
	ds_read_b128 v[124:127], v75 offset:37888
	ds_read_b128 v[128:131], v75 offset:38912
	ds_read_b128 v[140:143], v75 offset:39936
	s_waitcnt lgkmcnt(0)
	s_setprio 1
	s_barrier
	v_mfma_f32_16x16x32_bf16 v[64:67], v[68:71], v[104:107], v[64:67]
	v_mfma_f32_16x16x32_bf16 v[64:67], v[76:79], v[108:111], v[64:67]
	v_mfma_f32_16x16x32_bf16 v[60:63], v[80:83], v[104:107], v[60:63]
	v_mfma_f32_16x16x32_bf16 v[60:63], v[84:87], v[108:111], v[60:63]
	v_mfma_f32_16x16x32_bf16 v[48:51], v[68:71], v[112:115], v[48:51]
	v_mfma_f32_16x16x32_bf16 v[48:51], v[76:79], v[116:119], v[48:51]
	v_mfma_f32_16x16x32_bf16 v[44:47], v[80:83], v[112:115], v[44:47]
	v_mfma_f32_16x16x32_bf16 v[44:47], v[84:87], v[116:119], v[44:47]
	v_mfma_f32_16x16x32_bf16 v[30:33], v[68:71], v[120:123], v[30:33]
	v_mfma_f32_16x16x32_bf16 v[30:33], v[76:79], v[124:127], v[30:33]
	v_mfma_f32_16x16x32_bf16 v[26:29], v[80:83], v[120:123], v[26:29]
	v_mfma_f32_16x16x32_bf16 v[26:29], v[84:87], v[124:127], v[26:29]
	v_mfma_f32_16x16x32_bf16 v[14:17], v[68:71], v[128:131], v[14:17]
	v_mfma_f32_16x16x32_bf16 v[14:17], v[76:79], v[140:143], v[14:17]
	v_mfma_f32_16x16x32_bf16 v[10:13], v[80:83], v[128:131], v[10:13]
	v_mfma_f32_16x16x32_bf16 v[10:13], v[84:87], v[140:143], v[10:13]
	v_mfma_f32_16x16x32_bf16 v[56:59], v[88:91], v[104:107], v[56:59]
	v_mfma_f32_16x16x32_bf16 v[56:59], v[92:95], v[108:111], v[56:59]
	v_mfma_f32_16x16x32_bf16 v[52:55], v[96:99], v[104:107], v[52:55]
	v_mfma_f32_16x16x32_bf16 v[52:55], v[100:103], v[108:111], v[52:55]
	v_mfma_f32_16x16x32_bf16 v[40:43], v[88:91], v[112:115], v[40:43]
	v_mfma_f32_16x16x32_bf16 v[40:43], v[92:95], v[116:119], v[40:43]
	v_mfma_f32_16x16x32_bf16 v[36:39], v[96:99], v[112:115], v[36:39]
	v_mfma_f32_16x16x32_bf16 v[36:39], v[100:103], v[116:119], v[36:39]
	v_mfma_f32_16x16x32_bf16 v[22:25], v[88:91], v[120:123], v[22:25]
	v_mfma_f32_16x16x32_bf16 v[22:25], v[92:95], v[124:127], v[22:25]
	v_mfma_f32_16x16x32_bf16 v[18:21], v[96:99], v[120:123], v[18:21]
	v_mfma_f32_16x16x32_bf16 v[18:21], v[100:103], v[124:127], v[18:21]
	v_mfma_f32_16x16x32_bf16 v[6:9], v[88:91], v[128:131], v[6:9]
	v_mfma_f32_16x16x32_bf16 v[6:9], v[92:95], v[140:143], v[6:9]
	v_mfma_f32_16x16x32_bf16 v[2:5], v[96:99], v[128:131], v[2:5]
	v_mfma_f32_16x16x32_bf16 v[2:5], v[100:103], v[140:143], v[2:5]
	s_waitcnt vmcnt(0)
	s_barrier
	s_setprio 0
	s_add_i32 s44, s44, s22
	v_lshl_add_u64 v[68:69], v[72:73], 0, s[18:19]
	s_mov_b32 m0, s44
	s_nop 0
	global_load_lds_dwordx4 v[68:69], off
	s_add_i32 m0, s44, 0x2000
	s_add_u32 s16, s16, 0x18080
	v_lshl_add_u64 v[68:69], v[144:145], 0, s[18:19]
	s_addc_u32 s17, s17, 0
	s_add_i32 s44, s45, s22
	global_load_lds_dwordx4 v[68:69], off
	v_lshl_add_u64 v[68:69], s[16:17], 0, v[134:135]
	s_mov_b32 m0, s44
	s_nop 0
	global_load_lds_dwordx4 v[68:69], off
	v_lshl_add_u64 v[68:69], s[16:17], 0, v[138:139]
	s_add_i32 m0, s44, 0x2000
	s_nop 0
	global_load_lds_dwordx4 v[68:69], off
	v_lshl_add_u64 v[68:69], v[146:147], 0, s[18:19]
	s_mov_b32 m0, s25
	s_nop 0
	global_load_lds_dwordx4 v[68:69], off
	v_lshl_add_u64 v[68:69], v[148:149], 0, s[18:19]
	s_mov_b32 m0, s30
	s_nop 0
	global_load_lds_dwordx4 v[68:69], off
	s_barrier
	s_add_i32 s43, s43, 2
	s_add_u32 s20, s20, 0x100
	s_addc_u32 s21, s21, 0
	s_add_u32 s39, s39, 0x100
	s_addc_u32 s42, s42, 0
	s_cmp_gt_u32 s43, 3
	s_cbranch_scc0 .LBB0_1429
	s_and_b64 vcc, exec, s[10:11]
	s_cbranch_vccz .LBB0_1432
	s_barrier

.LBB0_1553:
	s_add_i32 s61, 0, 0x10000
	s_cmp_eq_u32 s60, 12
	s_cselect_b32 s63, s15, s37
	s_cselect_b32 s62, s17, s36
	s_cselect_b32 s35, s25, s43
	s_cselect_b32 s34, s27, s42
	s_add_i32 s66, 0, 0x14000
	v_add_u32_e32 v80, s61, v98
	v_add_u32_e32 v96, s66, v98
	ds_read_b128 v[68:71], v80
	ds_read_b128 v[72:75], v80 offset:1024
	ds_read_b128 v[76:79], v80 offset:2048
	ds_read_b128 v[80:83], v80 offset:3072
	ds_read_b128 v[84:87], v96
	ds_read_b128 v[88:91], v96 offset:1024
	ds_read_b128 v[92:95], v96 offset:2048
	ds_read_b128 v[100:103], v96 offset:3072
	ds_read_b128 v[104:107], v99
	ds_read_b128 v[108:111], v99 offset:1024
	ds_read_b128 v[112:115], v99 offset:2048
	ds_read_b128 v[116:119], v99 offset:3072
	ds_read_b128 v[120:123], v99 offset:4096
	ds_read_b128 v[124:127], v99 offset:5120
	ds_read_b128 v[128:131], v99 offset:6144
	ds_read_b128 v[132:135], v99 offset:7168
	s_waitcnt lgkmcnt(0)
	s_setprio 1
	s_barrier
	v_mfma_f32_16x16x32_bf16 v[60:63], v[68:71], v[104:107], v[60:63]
	v_mfma_f32_16x16x32_bf16 v[60:63], v[72:75], v[108:111], v[60:63]
	v_mfma_f32_16x16x32_bf16 v[48:51], v[76:79], v[104:107], v[48:51]
	v_mfma_f32_16x16x32_bf16 v[48:51], v[80:83], v[108:111], v[48:51]
	v_mfma_f32_16x16x32_bf16 v[52:55], v[68:71], v[112:115], v[52:55]
	v_mfma_f32_16x16x32_bf16 v[52:55], v[72:75], v[116:119], v[52:55]
	v_mfma_f32_16x16x32_bf16 v[44:47], v[76:79], v[112:115], v[44:47]
	v_mfma_f32_16x16x32_bf16 v[44:47], v[80:83], v[116:119], v[44:47]
	v_mfma_f32_16x16x32_bf16 v[30:33], v[68:71], v[120:123], v[30:33]
	v_mfma_f32_16x16x32_bf16 v[30:33], v[72:75], v[124:127], v[30:33]
	v_mfma_f32_16x16x32_bf16 v[26:29], v[76:79], v[120:123], v[26:29]
	v_mfma_f32_16x16x32_bf16 v[26:29], v[80:83], v[124:127], v[26:29]
	v_mfma_f32_16x16x32_bf16 v[14:17], v[68:71], v[128:131], v[14:17]
	v_mfma_f32_16x16x32_bf16 v[14:17], v[72:75], v[132:135], v[14:17]
	v_mfma_f32_16x16x32_bf16 v[10:13], v[76:79], v[128:131], v[10:13]
	v_mfma_f32_16x16x32_bf16 v[10:13], v[80:83], v[132:135], v[10:13]
	v_mfma_f32_16x16x32_bf16 v[64:67], v[84:87], v[104:107], v[64:67]
	v_mfma_f32_16x16x32_bf16 v[64:67], v[88:91], v[108:111], v[64:67]
	v_mfma_f32_16x16x32_bf16 v[56:59], v[92:95], v[104:107], v[56:59]
	v_mfma_f32_16x16x32_bf16 v[56:59], v[100:103], v[108:111], v[56:59]
	v_mfma_f32_16x16x32_bf16 v[40:43], v[84:87], v[112:115], v[40:43]
	v_mfma_f32_16x16x32_bf16 v[40:43], v[88:91], v[116:119], v[40:43]
	v_mfma_f32_16x16x32_bf16 v[36:39], v[92:95], v[112:115], v[36:39]
	v_mfma_f32_16x16x32_bf16 v[36:39], v[100:103], v[116:119], v[36:39]
	v_mfma_f32_16x16x32_bf16 v[22:25], v[84:87], v[120:123], v[22:25]
	v_mfma_f32_16x16x32_bf16 v[22:25], v[88:91], v[124:127], v[22:25]
	v_mfma_f32_16x16x32_bf16 v[18:21], v[92:95], v[120:123], v[18:21]
	v_mfma_f32_16x16x32_bf16 v[18:21], v[100:103], v[124:127], v[18:21]
	v_mfma_f32_16x16x32_bf16 v[6:9], v[84:87], v[128:131], v[6:9]
	v_mfma_f32_16x16x32_bf16 v[6:9], v[88:91], v[132:135], v[6:9]
	v_mfma_f32_16x16x32_bf16 v[2:5], v[92:95], v[128:131], v[2:5]
	v_mfma_f32_16x16x32_bf16 v[2:5], v[100:103], v[132:135], v[2:5]
	s_waitcnt vmcnt(0)
	s_barrier
	s_setprio 0
	s_add_i32 s61, s61, s44
	v_lshl_add_u64 v[96:97], s[34:35], 0, v[34:35]
	s_mov_b32 m0, s61
	v_lshl_add_u64 v[136:137], s[34:35], 0, v[152:153]
	global_load_lds_dwordx4 v[96:97], off
	s_add_i32 m0, s61, 0x2000
	s_add_u32 s64, s34, 0x40000
	s_addc_u32 s65, s35, 0
	s_add_i32 s61, s66, s44
	global_load_lds_dwordx4 v[136:137], off
	v_lshl_add_u64 v[68:69], s[64:65], 0, v[34:35]
	s_mov_b32 m0, s61
	v_lshl_add_u64 v[138:139], s[62:63], 0, v[148:149]
	global_load_lds_dwordx4 v[68:69], off
	v_lshl_add_u64 v[68:69], s[64:65], 0, v[152:153]
	s_add_i32 m0, s61, 0x2000
	v_lshl_add_u64 v[140:141], s[62:63], 0, v[150:151]
	global_load_lds_dwordx4 v[68:69], off
	s_mov_b32 m0, s45
	s_nop 0
	global_load_lds_dwordx4 v[138:139], off
	s_mov_b32 m0, s46
	s_nop 0
	global_load_lds_dwordx4 v[140:141], off
	s_barrier
	s_add_i32 s61, 0, 0x18000
	s_add_i32 s62, 0, 0x1c000
	v_add_u32_e32 v80, s61, v98
	v_add_u32_e32 v100, s62, v98
	ds_read_b128 v[68:71], v80
	ds_read_b128 v[72:75], v80 offset:1024
	ds_read_b128 v[76:79], v80 offset:2048
	ds_read_b128 v[80:83], v80 offset:3072
	ds_read_b128 v[84:87], v100
	ds_read_b128 v[88:91], v100 offset:1024
	ds_read_b128 v[92:95], v100 offset:2048
	ds_read_b128 v[100:103], v100 offset:3072
	ds_read_b128 v[104:107], v99 offset:32768
	ds_read_b128 v[108:111], v99 offset:33792
	ds_read_b128 v[112:115], v99 offset:34816
	ds_read_b128 v[116:119], v99 offset:35840
	ds_read_b128 v[120:123], v99 offset:36864
	ds_read_b128 v[124:127], v99 offset:37888
	ds_read_b128 v[128:131], v99 offset:38912
	ds_read_b128 v[132:135], v99 offset:39936
	s_waitcnt lgkmcnt(0)
	s_setprio 1
	s_barrier
	v_mfma_f32_16x16x32_bf16 v[60:63], v[68:71], v[104:107], v[60:63]
	v_mfma_f32_16x16x32_bf16 v[60:63], v[72:75], v[108:111], v[60:63]
	v_mfma_f32_16x16x32_bf16 v[48:51], v[76:79], v[104:107], v[48:51]
	v_mfma_f32_16x16x32_bf16 v[48:51], v[80:83], v[108:111], v[48:51]
	v_mfma_f32_16x16x32_bf16 v[52:55], v[68:71], v[112:115], v[52:55]
	v_mfma_f32_16x16x32_bf16 v[52:55], v[72:75], v[116:119], v[52:55]
	v_mfma_f32_16x16x32_bf16 v[44:47], v[76:79], v[112:115], v[44:47]
	v_mfma_f32_16x16x32_bf16 v[44:47], v[80:83], v[116:119], v[44:47]
	v_mfma_f32_16x16x32_bf16 v[30:33], v[68:71], v[120:123], v[30:33]
	v_mfma_f32_16x16x32_bf16 v[30:33], v[72:75], v[124:127], v[30:33]
	v_mfma_f32_16x16x32_bf16 v[26:29], v[76:79], v[120:123], v[26:29]
	v_mfma_f32_16x16x32_bf16 v[26:29], v[80:83], v[124:127], v[26:29]
	v_mfma_f32_16x16x32_bf16 v[14:17], v[68:71], v[128:131], v[14:17]
	v_mfma_f32_16x16x32_bf16 v[14:17], v[72:75], v[132:135], v[14:17]
	v_mfma_f32_16x16x32_bf16 v[10:13], v[76:79], v[128:131], v[10:13]
	v_mfma_f32_16x16x32_bf16 v[10:13], v[80:83], v[132:135], v[10:13]
	v_mfma_f32_16x16x32_bf16 v[64:67], v[84:87], v[104:107], v[64:67]
	v_mfma_f32_16x16x32_bf16 v[64:67], v[88:91], v[108:111], v[64:67]
	v_mfma_f32_16x16x32_bf16 v[56:59], v[92:95], v[104:107], v[56:59]
	v_mfma_f32_16x16x32_bf16 v[56:59], v[100:103], v[108:111], v[56:59]
	v_mfma_f32_16x16x32_bf16 v[40:43], v[84:87], v[112:115], v[40:43]
	v_mfma_f32_16x16x32_bf16 v[40:43], v[88:91], v[116:119], v[40:43]
	v_mfma_f32_16x16x32_bf16 v[36:39], v[92:95], v[112:115], v[36:39]
	v_mfma_f32_16x16x32_bf16 v[36:39], v[100:103], v[116:119], v[36:39]
	v_mfma_f32_16x16x32_bf16 v[22:25], v[84:87], v[120:123], v[22:25]
	v_mfma_f32_16x16x32_bf16 v[22:25], v[88:91], v[124:127], v[22:25]
	v_mfma_f32_16x16x32_bf16 v[18:21], v[92:95], v[120:123], v[18:21]
	v_mfma_f32_16x16x32_bf16 v[18:21], v[100:103], v[124:127], v[18:21]
	v_mfma_f32_16x16x32_bf16 v[6:9], v[84:87], v[128:131], v[6:9]
	v_mfma_f32_16x16x32_bf16 v[6:9], v[88:91], v[132:135], v[6:9]
	v_mfma_f32_16x16x32_bf16 v[2:5], v[92:95], v[128:131], v[2:5]
	v_mfma_f32_16x16x32_bf16 v[2:5], v[100:103], v[132:135], v[2:5]
	s_waitcnt vmcnt(0)
	s_barrier
	s_setprio 0
	s_add_i32 s61, s61, s44
	v_lshl_add_u64 v[68:69], v[96:97], 0, s[18:19]
	s_mov_b32 m0, s61
	s_nop 0
	global_load_lds_dwordx4 v[68:69], off
	s_add_i32 m0, s61, 0x2000
	s_add_u32 s34, s34, 0x40080
	v_lshl_add_u64 v[68:69], v[136:137], 0, s[18:19]
	s_addc_u32 s35, s35, 0
	s_add_i32 s61, s62, s44
	global_load_lds_dwordx4 v[68:69], off
	v_lshl_add_u64 v[68:69], s[34:35], 0, v[34:35]
	s_mov_b32 m0, s61
	s_nop 0
	global_load_lds_dwordx4 v[68:69], off
	v_lshl_add_u64 v[68:69], s[34:35], 0, v[152:153]
	s_add_i32 m0, s61, 0x2000
	s_nop 0
	global_load_lds_dwordx4 v[68:69], off
	v_lshl_add_u64 v[68:69], v[138:139], 0, s[18:19]
	s_mov_b32 m0, s47
	s_nop 0
	global_load_lds_dwordx4 v[68:69], off
	v_lshl_add_u64 v[68:69], v[140:141], 0, s[18:19]
	s_mov_b32 m0, s54
	s_nop 0
	global_load_lds_dwordx4 v[68:69], off
	s_barrier
	s_add_i32 s60, s60, 2
	s_add_u32 s36, s36, 0x100
	s_addc_u32 s37, s37, 0
	s_add_u32 s42, s42, 0x100
	s_addc_u32 s43, s43, 0
	s_cmp_gt_u32 s60, 13
	s_cbranch_scc0 .LBB0_1553
	s_and_b64 vcc, exec, s[22:23]
	s_cbranch_vccz .LBB0_1556
	s_barrier

.LBB0_1683:
	v_mfma_f32_16x16x32_bf16 v[130:133], v[166:169], v[190:193], v[130:133]
	v_mfma_f32_16x16x32_bf16 v[130:133], v[170:173], v[194:197], v[130:133]
	v_mfma_f32_16x16x32_bf16 v[126:129], v[174:177], v[190:193], v[126:129]
	v_mfma_f32_16x16x32_bf16 v[126:129], v[178:181], v[194:197], v[126:129]
	v_mfma_f32_16x16x32_bf16 v[114:117], v[166:169], v[182:185], v[114:117]
	v_mfma_f32_16x16x32_bf16 v[114:117], v[170:173], v[186:189], v[114:117]
	v_mfma_f32_16x16x32_bf16 v[110:113], v[174:177], v[182:185], v[110:113]
	v_mfma_f32_16x16x32_bf16 v[110:113], v[178:181], v[186:189], v[110:113]
	v_mfma_f32_16x16x32_bf16 v[98:101], v[166:169], v[158:161], v[98:101]
	v_mfma_f32_16x16x32_bf16 v[98:101], v[170:173], v[162:165], v[98:101]
	v_mfma_f32_16x16x32_bf16 v[94:97], v[174:177], v[158:161], v[94:97]
	v_mfma_f32_16x16x32_bf16 v[94:97], v[178:181], v[162:165], v[94:97]
	v_mfma_f32_16x16x32_bf16 v[82:85], v[166:169], v[150:153], v[82:85]
	v_mfma_f32_16x16x32_bf16 v[82:85], v[170:173], v[154:157], v[82:85]
	v_mfma_f32_16x16x32_bf16 v[78:81], v[174:177], v[150:153], v[78:81]
	v_mfma_f32_16x16x32_bf16 v[78:81], v[178:181], v[154:157], v[78:81]
	v_mfma_f32_16x16x32_bf16 v[122:125], v[134:137], v[190:193], v[122:125]
	v_mfma_f32_16x16x32_bf16 v[122:125], v[138:141], v[194:197], v[122:125]
	v_mfma_f32_16x16x32_bf16 v[118:121], v[142:145], v[190:193], v[118:121]
	v_mfma_f32_16x16x32_bf16 v[118:121], v[146:149], v[194:197], v[118:121]
	v_mfma_f32_16x16x32_bf16 v[106:109], v[134:137], v[182:185], v[106:109]
	v_mfma_f32_16x16x32_bf16 v[106:109], v[138:141], v[186:189], v[106:109]
	v_mfma_f32_16x16x32_bf16 v[102:105], v[142:145], v[182:185], v[102:105]
	v_mfma_f32_16x16x32_bf16 v[102:105], v[146:149], v[186:189], v[102:105]
	v_mfma_f32_16x16x32_bf16 v[90:93], v[134:137], v[158:161], v[90:93]
	v_mfma_f32_16x16x32_bf16 v[90:93], v[138:141], v[162:165], v[90:93]
	v_mfma_f32_16x16x32_bf16 v[86:89], v[142:145], v[158:161], v[86:89]
	v_mfma_f32_16x16x32_bf16 v[86:89], v[146:149], v[162:165], v[86:89]
	v_mfma_f32_16x16x32_bf16 v[74:77], v[134:137], v[150:153], v[74:77]
	v_mfma_f32_16x16x32_bf16 v[74:77], v[138:141], v[154:157], v[74:77]
	v_mfma_f32_16x16x32_bf16 v[70:73], v[142:145], v[150:153], v[70:73]
	v_mfma_f32_16x16x32_bf16 v[70:73], v[146:149], v[154:157], v[70:73]
	s_waitcnt vmcnt(0)
	s_barrier
	s_setprio 0
	s_mov_b32 m0, s54
	v_lshl_add_u64 v[36:37], s[36:37], 0, v[210:211]
	s_add_u32 vcc_lo, s36, 0x80000
	global_load_lds_dwordx4 v[36:37], off
	v_lshl_add_u64 v[198:199], s[36:37], 0, v[214:215]
	s_mov_b32 m0, s55
	s_addc_u32 vcc_hi, s37, 0
	global_load_lds_dwordx4 v[198:199], off
	v_lshl_add_u64 v[134:135], vcc, 0, v[210:211]
	s_mov_b32 m0, s59
	v_lshl_add_u64 v[200:201], s[78:79], 0, v[208:209]
	global_load_lds_dwordx4 v[134:135], off
	v_lshl_add_u64 v[134:135], vcc, 0, v[214:215]
	s_mov_b32 m0, s60
	v_lshl_add_u64 v[222:223], s[78:79], 0, v[212:213]
	global_load_lds_dwordx4 v[134:135], off
	s_mov_b32 m0, s43
	s_nop 0
	global_load_lds_dwordx4 v[200:201], off
	s_mov_b32 m0, s61
	s_nop 0
	global_load_lds_dwordx4 v[222:223], off
	s_barrier
	s_add_i32 s77, 0, 0x18000
	v_add_u32_e32 v34, s77, v220
	s_add_i32 s78, 0, 0x1c000
	ds_read_b128 v[134:137], v34
	ds_read_b128 v[138:141], v34 offset:1024
	ds_read_b128 v[142:145], v34 offset:2048
	ds_read_b128 v[146:149], v34 offset:3072
	v_add_u32_e32 v34, s78, v220
	ds_read_b128 v[150:153], v34
	ds_read_b128 v[154:157], v34 offset:1024
	ds_read_b128 v[158:161], v34 offset:2048
	ds_read_b128 v[162:165], v34 offset:3072
	ds_read_b128 v[166:169], v207 offset:32768
	ds_read_b128 v[170:173], v207 offset:33792
	ds_read_b128 v[174:177], v207 offset:34816
	ds_read_b128 v[178:181], v207 offset:35840
	ds_read_b128 v[182:185], v207 offset:36864
	ds_read_b128 v[186:189], v207 offset:37888
	ds_read_b128 v[190:193], v207 offset:38912
	ds_read_b128 v[194:197], v207 offset:39936
	s_waitcnt lgkmcnt(0)
	s_setprio 1
	s_barrier
	v_mfma_f32_16x16x32_bf16 v[130:133], v[134:137], v[166:169], v[130:133]
	v_mfma_f32_16x16x32_bf16 v[130:133], v[138:141], v[170:173], v[130:133]
	v_mfma_f32_16x16x32_bf16 v[126:129], v[142:145], v[166:169], v[126:129]
	v_mfma_f32_16x16x32_bf16 v[126:129], v[146:149], v[170:173], v[126:129]
	v_mfma_f32_16x16x32_bf16 v[114:117], v[134:137], v[174:177], v[114:117]
	v_mfma_f32_16x16x32_bf16 v[114:117], v[138:141], v[178:181], v[114:117]
	v_mfma_f32_16x16x32_bf16 v[110:113], v[142:145], v[174:177], v[110:113]
	v_mfma_f32_16x16x32_bf16 v[110:113], v[146:149], v[178:181], v[110:113]
	v_mfma_f32_16x16x32_bf16 v[98:101], v[134:137], v[182:185], v[98:101]
	v_mfma_f32_16x16x32_bf16 v[98:101], v[138:141], v[186:189], v[98:101]
	v_mfma_f32_16x16x32_bf16 v[94:97], v[142:145], v[182:185], v[94:97]
	v_mfma_f32_16x16x32_bf16 v[94:97], v[146:149], v[186:189], v[94:97]
	v_mfma_f32_16x16x32_bf16 v[82:85], v[134:137], v[190:193], v[82:85]
	v_mfma_f32_16x16x32_bf16 v[82:85], v[138:141], v[194:197], v[82:85]
	v_mfma_f32_16x16x32_bf16 v[78:81], v[142:145], v[190:193], v[78:81]
	v_mfma_f32_16x16x32_bf16 v[78:81], v[146:149], v[194:197], v[78:81]
	v_mfma_f32_16x16x32_bf16 v[122:125], v[150:153], v[166:169], v[122:125]
	v_mfma_f32_16x16x32_bf16 v[122:125], v[154:157], v[170:173], v[122:125]
	v_mfma_f32_16x16x32_bf16 v[118:121], v[158:161], v[166:169], v[118:121]
	v_mfma_f32_16x16x32_bf16 v[118:121], v[162:165], v[170:173], v[118:121]
	v_mfma_f32_16x16x32_bf16 v[106:109], v[150:153], v[174:177], v[106:109]
	v_mfma_f32_16x16x32_bf16 v[106:109], v[154:157], v[178:181], v[106:109]
	v_mfma_f32_16x16x32_bf16 v[102:105], v[158:161], v[174:177], v[102:105]
	v_mfma_f32_16x16x32_bf16 v[102:105], v[162:165], v[178:181], v[102:105]
	v_mfma_f32_16x16x32_bf16 v[90:93], v[150:153], v[182:185], v[90:93]
	v_mfma_f32_16x16x32_bf16 v[90:93], v[154:157], v[186:189], v[90:93]
	v_mfma_f32_16x16x32_bf16 v[86:89], v[158:161], v[182:185], v[86:89]
	v_mfma_f32_16x16x32_bf16 v[86:89], v[162:165], v[186:189], v[86:89]
	v_mfma_f32_16x16x32_bf16 v[74:77], v[150:153], v[190:193], v[74:77]
	v_mfma_f32_16x16x32_bf16 v[74:77], v[154:157], v[194:197], v[74:77]
	v_mfma_f32_16x16x32_bf16 v[70:73], v[158:161], v[190:193], v[70:73]
	v_mfma_f32_16x16x32_bf16 v[70:73], v[162:165], v[194:197], v[70:73]
	s_waitcnt vmcnt(0)
	s_barrier
	s_setprio 0
	s_add_i32 s77, s77, s42
	v_lshl_add_u64 v[36:37], v[36:37], 0, s[18:19]
	s_mov_b32 m0, s77
	s_nop 0
	global_load_lds_dwordx4 v[36:37], off
	s_add_i32 m0, s77, 0x2000
	s_add_u32 s36, s36, 0x80080
	v_lshl_add_u64 v[36:37], v[198:199], 0, s[18:19]
	s_addc_u32 s37, s37, 0
	s_add_i32 s77, s78, s42
	global_load_lds_dwordx4 v[36:37], off
	v_lshl_add_u64 v[36:37], s[36:37], 0, v[210:211]
	s_mov_b32 m0, s77
	s_nop 0
	global_load_lds_dwordx4 v[36:37], off
	v_lshl_add_u64 v[36:37], s[36:37], 0, v[214:215]
	s_add_i32 m0, s77, 0x2000
	s_nop 0
	global_load_lds_dwordx4 v[36:37], off
	v_lshl_add_u64 v[36:37], v[200:201], 0, s[18:19]
	s_mov_b32 m0, s62
	s_nop 0
	global_load_lds_dwordx4 v[36:37], off
	v_lshl_add_u64 v[36:37], v[222:223], 0, s[18:19]
	s_mov_b32 m0, s63
	s_nop 0
	global_load_lds_dwordx4 v[36:37], off
	s_barrier
	s_add_i32 s76, s76, 2
	s_add_u32 s40, s40, 0x100
	s_addc_u32 s41, s41, 0
	s_add_u32 s74, s74, 0x100
	s_addc_u32 s75, s75, 0
	s_cmp_gt_u32 s76, 29
	s_cbranch_scc1 .LBB0_1690

.LBB0_1688:
	v_add_u32_e32 v34, 0, v220
	v_add_u32_e32 v36, 0x10000, v34
	v_add_u32_e32 v34, 0x14000, v34
	ds_read_b128 v[166:169], v36
	ds_read_b128 v[170:173], v36 offset:1024
	ds_read_b128 v[174:177], v36 offset:2048
	ds_read_b128 v[178:181], v36 offset:3072
	ds_read_b128 v[134:137], v34
	ds_read_b128 v[138:141], v34 offset:1024
	ds_read_b128 v[142:145], v34 offset:2048
	ds_read_b128 v[146:149], v34 offset:3072
	ds_read_b128 v[190:193], v207
	ds_read_b128 v[194:197], v207 offset:1024
	ds_read_b128 v[182:185], v207 offset:2048
	ds_read_b128 v[186:189], v207 offset:3072
	ds_read_b128 v[158:161], v207 offset:4096
	ds_read_b128 v[162:165], v207 offset:5120
	ds_read_b128 v[150:153], v207 offset:6144
	ds_read_b128 v[154:157], v207 offset:7168
	s_waitcnt lgkmcnt(0)
	s_cmp_lg_u32 s76, -2
	s_cmp_eq_u32 s76, 28
	s_cselect_b32 s79, s13, s41
	s_cselect_b32 s78, s25, s40
	s_cselect_b32 s37, s23, s75
	s_cselect_b32 s36, s52, s74
	s_cmp_lg_u32 s76, -2
	s_setprio 1
	s_barrier
	s_cbranch_scc1 .LBB0_1683
	s_add_i32 m0, s43, 0x21200
	s_nop 0
	global_load_lds_dwordx4 v[218:219], off
	s_branch .LBB0_1683
